# decode attention: f32 K/V cache stream 1.5 steps ahead through a 24-quad register ring (per-quad vmcnt(23) waits, immediate re-request via saddr loads) instead of 1 step ahead with a blanket wait
# baseline (speedup 1.0000x reference)
; #define LAS __attribute__((address_space(3)))
; #define CACHE_K IN_(2)
; #define CACHE_V IN_(3)
; #define DA_LOAD(st) do { const float* kb_ = Kc + (size_t)(st) * 131072; const float* vb_ = Vc + (size_t)(st) * 131072; \
;         _Pragma("unroll") for (int i = 0; i < 8; ++i) { kx[i] = __builtin_nontemporal_load((const v4f*)(kb_ + i * 16384 + voff)); vx[i] = __builtin_nontemporal_load((const v4f*)(vb_ + i * 16384 + voff)); } } while (0)
; DI void decode_unit(Ctx A_, LAS unsigned char* lds, int b, int h, float lam, int wave, int lane, int tid) {
;     const int r = lane & 31, hh = lane >> 5, mp = wave >> 2, kr = wave & 3;
;     bf16* P = P_;
;     LAS float* wsf = (LAS float*)(lds + WSF_OFF) + wave * 128;
;     const float* Kc = CACHE_K + ((size_t)b * PAST * 8 + h) * 128; const float* Vc = CACHE_V + ((size_t)b * PAST * 8 + h) * 128;
;     const size_t rowq = (size_t)MP + b * DS;
;     v4f kx[8], vx[8];
;     const unsigned voff = (unsigned)((tid >> 5) * 1024 + (tid & 31) * 4);
;     ...
;     DA_LOAD(0);
;     const int c4_ = tid & 31, kk_ = tid >> 5;
;     LAS unsigned char* kw = lds + (c4_ >> 1) * CS + kk_ * 16 + (c4_ & 1) * 8;
;     LAS unsigned char* vw = lds + VOFF + (c4_ >> 3) * PS + kk_ * 64 + (c4_ & 7) * 8;
;     bf16x8 qr[4];
;     { const bf16* Qg = P + (rowq + (r & 15)) * PLD + C_QA + h * 128 + mp * 64 + hh * 8;
; #pragma unroll
;       for (int d0 = 0; d0 < 4; ++d0) { const v4u w = *(const v4u*)(Qg + d0 * 16); const v4u z = {0u, 0u, 0u, 0u}; qr[d0] = __builtin_bit_cast(bf16x8, r < 16 ? w : z); } }
.LBB0_825:
	s_or_b64 exec, exec, s[4:5]
	s_lshl_b32 s2, s2, 2
	s_add_i32 s2, s2, 0
	s_add_i32 s2, s2, 0x20040
	v_mov_b32_e32 v2, s2
	s_waitcnt lgkmcnt(0)
	s_barrier
	ds_read_b32 v2, v2
	s_mov_b64 s[4:5], -1
	s_waitcnt lgkmcnt(0)
	v_readfirstlane_b32 s2, v2
	v_mov_b32_e32 v208, s2
	s_cmpk_gt_i32 s2, 0xff
	s_cbranch_scc1 .LBB0_820
	s_ashr_i32 s4, s2, 3
	s_lshl_b32 s2, s2, 7
	s_ashr_i32 s5, s4, 31
	s_and_b32 s60, s2, 0x380
	s_lshl_b64 s[6:7], s[4:5], 24
	s_lshl_b32 s2, s60, 2
	v_readlane_b32 s64, v254, 2
	v_mov_b32 v22, v0
	s_or_b32 s2, s6, s2
	v_and_b32_e32 v164, 31, v22
	v_readlane_b32 s68, v254, 6
	v_readlane_b32 s69, v254, 7
	s_add_u32 s8, s68, s2
	v_ashrrev_i32_e32 v23, 5, v22
	v_lshlrev_b32_e32 v180, 2, v164
	v_readlane_b32 s70, v254, 8
	s_addc_u32 s9, s69, s7
	v_lshl_or_b32 v162, v23, 10, v180
	v_lshlrev_b32_e32 v248, 2, v162
	v_readlane_b32 s71, v254, 9
	s_add_u32 s6, s70, s2
	v_lshlrev_b64 v[2:3], 2, v[162:163]
	s_addc_u32 s7, s71, s7
	s_add_u32 s98, s8, 0x80000
	s_addc_u32 s99, s9, 0
	s_add_u32 s100, s6, 0x80000
	s_addc_u32 s101, s7, 0
	v_lshl_add_u64 v[166:167], s[8:9], 0, v[2:3]
	v_lshl_add_u64 v[168:169], s[6:7], 0, v[2:3]
	v_add_co_u32_e32 v2, vcc, s26, v166
	global_load_dwordx4 v[82:85], v[166:167], off nt
	global_load_dwordx4 v[86:89], v[168:169], off nt
	v_addc_co_u32_e32 v3, vcc, 0, v167, vcc
	global_load_dwordx4 v[90:93], v[2:3], off nt
	v_add_co_u32_e32 v2, vcc, s26, v168
	s_lshl_b32 s2, s4, 4
	s_nop 0
	v_addc_co_u32_e32 v3, vcc, 0, v169, vcc
	global_load_dwordx4 v[94:97], v[2:3], off nt
	v_add_co_u32_e32 v2, vcc, s46, v166
	s_ashr_i32 s4, s2, 31
	s_nop 0
	v_addc_co_u32_e32 v3, vcc, 0, v167, vcc
	global_load_dwordx4 v[98:101], v[2:3], off nt
	v_add_co_u32_e32 v2, vcc, s46, v168
	s_add_u32 s61, s2, 0x8000
	s_nop 0
	v_addc_co_u32_e32 v3, vcc, 0, v169, vcc
	global_load_dwordx4 v[102:105], v[2:3], off nt
	v_add_co_u32_e32 v2, vcc, s47, v166
	s_addc_u32 s59, s4, 0
	s_nop 0
	v_addc_co_u32_e32 v3, vcc, 0, v167, vcc
	global_load_dwordx4 v[106:109], v[2:3], off nt
	v_add_co_u32_e32 v2, vcc, s47, v168
	v_readlane_b32 s4, v255, 9
	s_nop 0
	v_addc_co_u32_e32 v3, vcc, 0, v169, vcc
	global_load_dwordx4 v[110:113], v[2:3], off nt
	v_add_co_u32_e32 v2, vcc, s48, v166
	v_and_b32_e32 v24, 15, v22
	s_nop 0
	v_addc_co_u32_e32 v3, vcc, 0, v167, vcc
	global_load_dwordx4 v[114:117], v[2:3], off nt
	v_add_co_u32_e32 v2, vcc, s48, v168
	v_readlane_b32 s5, v255, 10
	s_nop 0
	v_addc_co_u32_e32 v3, vcc, 0, v169, vcc
	global_load_dwordx4 v[118:121], v[2:3], off nt
	v_or_b32_e32 v2, s61, v24
	v_mov_b64_e32 v[18:19], s[4:5]
	v_add_co_u32_e32 v10, vcc, s49, v166
	v_mad_u64_u32 v[2:3], s[4:5], v2, s53, v[18:19]
	s_nop 0
	v_addc_co_u32_e32 v11, vcc, 0, v167, vcc
	v_mad_i32_i24 v3, s59, v174, v3
	s_lshl_b32 s2, s60, 1
	v_add_co_u32_e32 v16, vcc, s49, v168
	v_bfe_u32 v179, v22, 5, 1
	v_lshl_add_u64 v[2:3], v[2:3], 0, s[2:3]
	v_addc_co_u32_e32 v17, vcc, 0, v169, vcc
	v_lshl_add_u64 v[2:3], s[10:11], 1, v[2:3]
	v_lshlrev_b32_e32 v162, 4, v179
	v_add_co_u32_e32 v20, vcc, s50, v166
	v_lshl_add_u64 v[14:15], v[2:3], 0, v[162:163]
	s_nop 0
	v_addc_co_u32_e32 v21, vcc, 0, v167, vcc
	global_load_dwordx4 v[2:5], v[14:15], off
	global_load_dwordx4 v[6:9], v[14:15], off offset:32
	global_load_dwordx4 v[130:133], v[10:11], off nt
	s_nop 0
	global_load_dwordx4 v[10:13], v[14:15], off offset:64
	global_load_dwordx4 v[138:141], v[16:17], off nt
	s_nop 0
	global_load_dwordx4 v[14:17], v[14:15], off offset:96
	v_bfe_u32 v26, v22, 3, 2
	global_load_dwordx4 v[146:149], v[20:21], off nt
	v_add_co_u32_e32 v20, vcc, s50, v168
	v_mul_u32_u24_e32 v26, 0x820, v26
	s_nop 0
	v_addc_co_u32_e32 v21, vcc, 0, v169, vcc
	global_load_dwordx4 v[150:153], v[20:21], off nt
	v_add_co_u32_e32 v20, vcc, s51, v166
	s_movk_i32 s6, 0x100
	s_nop 0
	v_addc_co_u32_e32 v21, vcc, 0, v167, vcc
	global_load_dwordx4 v[154:157], v[20:21], off nt
	v_add_co_u32_e32 v20, vcc, s51, v168
	v_lshlrev_b32_e32 v25, 3, v22
	s_nop 0
	v_addc_co_u32_e32 v21, vcc, 0, v169, vcc
	global_load_dwordx4 v[158:161], v[20:21], off nt
	v_bfe_u32 v20, v22, 1, 4
	v_lshlrev_b32_e32 v21, 4, v23
	v_lshlrev_b32_e32 v23, 6, v23
	v_mul_u32_u24_e32 v20, 0x210, v20
	v_add3_u32 v37, 0, v26, v23
	v_bfe_u32 v23, v22, 4, 4
	v_add3_u32 v36, 0, v20, v21
	v_or_b32_e32 v20, s61, v23
	v_mad_u64_u32 v[18:19], s[4:5], v20, s53, v[18:19]
	v_cmp_gt_i32_e32 vcc, s6, v22
	v_mad_i32_i24 v19, s59, v174, v19
	v_mov_b32_e32 v21, v163
	v_cndmask_b32_e32 v20, v175, v176, vcc
	v_lshl_add_u64 v[18:19], v[18:19], 0, v[20:21]
	v_lshlrev_b32_e32 v26, 4, v22
	v_lshl_add_u64 v[18:19], v[18:19], 0, s[2:3]
	v_and_b32_e32 v20, 0xf0, v26
	v_lshl_add_u64 v[170:171], v[18:19], 0, v[20:21]
	v_bfe_u32 v18, v22, 2, 2
	v_mul_u32_u24_e32 v18, 0x820, v18
	v_lshlrev_b32_e32 v19, 6, v23
	v_add3_u32 v38, 0, v18, v19
	v_or_b32_e32 v18, s24, v179
	v_mul_lo_u32 v18, v18, s52
	v_add_u32_e32 v42, s23, v18
	v_lshlrev_b32_e32 v18, 1, v22
	v_and_b32_e32 v18, 32, v18
	v_add_u32_e32 v18, s25, v18
	v_and_b32_e32 v19, 24, v25
	v_lshlrev_b32_e32 v20, 8, v179
	v_and_b32_e32 v34, 8, v25
	v_and_b32_e32 v35, 56, v25
	s_movk_i32 s4, 0xff
	v_and_b32_e32 v39, 48, v26
	v_mad_u32_u24 v40, v24, s52, 0
	v_lshlrev_b32_e32 v41, 4, v23
	v_lshlrev_b32_e32 v43, 4, v164
	v_and_b32_e32 v44, 0xc0, v26
	v_add3_u32 v45, v18, v19, v20
	v_cmp_gt_u32_e32 vcc, 16, v164
	v_mov_b32_e32 v18, v163
	v_mov_b32_e32 v19, v163
	v_mov_b32_e32 v32, v163
	v_mov_b32_e32 v33, v163
	v_and_b32_e32 v165, 63, v22
	v_cmp_lt_i32_e64 s[4:5], s4, v22
	v_mov_b32_e32 v20, v163
	v_mov_b32_e32 v22, v163
	v_mov_b32_e32 v23, v163
	v_mov_b32_e32 v24, v163
	v_mov_b32_e32 v25, v163
	v_mov_b32_e32 v26, v163
	v_mov_b32_e32 v27, v163
	v_mov_b32_e32 v28, v163
	v_mov_b32_e32 v29, v163
	s_waitcnt vmcnt(8)
; DI void decode_unit(Ctx A_, LAS unsigned char* lds, int b, int h, float lam, int wave, int lane, int tid) {
;     ...
;       for (int d0 = 0; d0 < 4; ++d0) { const v4u w = *(const v4u*)(Qg + d0 * 16); const v4u z = {0u, 0u, 0u, 0u}; qr[d0] = __builtin_bit_cast(bf16x8, r < 16 ? w : z); } }
;     f32x16 o[4];
; #pragma unroll
;     for (int nb = 0; nb < 4; ++nb)
; #pragma unroll
;         for (int i = 0; i < 16; ++i) o[nb][i] = 0.f;
;     float m = -INFINITY, l = 0.f;
;     const int g16 = (lane >> 4) & 1, p4 = lane & 3, q4 = (lane & 15) >> 2;
; #pragma unroll 1
;     for (int st = 0; st <= PAST / 128; ++st) {
;         const bool last = st == PAST / 128;
;         v4u nw = {0u, 0u, 0u, 0u};
;         if (last) {
;             const int t2 = tid & 255, key = t2 >> 4, c8 = t2 & 15;
;             nw = *(const v4u*)(P + (rowq + key) * PLD + (tid < 256 ? C_KA : C_VA) + h * 128 + c8 * 8);
;         }
	v_cndmask_b32_e32 v129, 0, v9, vcc
	v_cndmask_b32_e32 v125, 0, v5, vcc
	v_cndmask_b32_e32 v124, 0, v4, vcc
	v_cndmask_b32_e32 v123, 0, v3, vcc
	v_cndmask_b32_e32 v122, 0, v2, vcc
	v_cndmask_b32_e32 v128, 0, v8, vcc
	v_cndmask_b32_e32 v127, 0, v7, vcc
	v_cndmask_b32_e32 v126, 0, v6, vcc
	s_waitcnt vmcnt(6)
	v_cndmask_b32_e32 v137, 0, v13, vcc
	v_cndmask_b32_e32 v136, 0, v12, vcc
	v_cndmask_b32_e32 v135, 0, v11, vcc
	v_cndmask_b32_e32 v134, 0, v10, vcc
	s_waitcnt vmcnt(4)
	v_cndmask_b32_e32 v145, 0, v17, vcc
	v_cndmask_b32_e32 v144, 0, v16, vcc
	v_cndmask_b32_e32 v143, 0, v15, vcc
	v_cndmask_b32_e32 v142, 0, v14, vcc
	v_mov_b32_e32 v30, v163
	v_mov_b32_e32 v31, v163
	v_add_u32_e32 v183, v38, v39
	v_add_u32_e32 v184, v40, v41
	v_add_u32_e32 v185, v36, v34
	v_add_u32_e32 v186, v37, v35
	v_add_u32_e32 v187, v42, v43
	v_add_u32_e32 v188, v45, v44
	v_mov_b64_e32 v[64:65], v[32:33]
	v_mov_b64_e32 v[48:49], v[32:33]
	v_mov_b64_e32 v[2:3], v[18:19]
	s_mov_b32 s62, 0
	v_cmp_gt_u32_e64 s[8:9], 32, v165
	v_add_u32_e32 v181, s22, v180
	v_mov_b32_e32 v182, 0
	v_mov_b32_e32 v189, 0xff800000
	s_mov_b64 s[16:17], 0
	v_mov_b64_e32 v[62:63], v[30:31]
	v_mov_b64_e32 v[60:61], v[28:29]
	v_mov_b64_e32 v[58:59], v[26:27]
	v_mov_b64_e32 v[56:57], v[24:25]
	v_mov_b64_e32 v[54:55], v[22:23]
	v_mov_b64_e32 v[52:53], v[20:21]
	v_mov_b64_e32 v[50:51], v[18:19]
	v_mov_b64_e32 v[46:47], v[30:31]
	v_mov_b64_e32 v[44:45], v[28:29]
	v_mov_b64_e32 v[42:43], v[26:27]
	v_mov_b64_e32 v[40:41], v[24:25]
	v_mov_b64_e32 v[38:39], v[22:23]
	v_mov_b64_e32 v[36:37], v[20:21]
	v_mov_b64_e32 v[34:35], v[18:19]
	v_mov_b64_e32 v[4:5], v[20:21]
	v_mov_b64_e32 v[6:7], v[22:23]
	v_mov_b64_e32 v[8:9], v[24:25]
	v_mov_b64_e32 v[10:11], v[26:27]
	v_mov_b64_e32 v[12:13], v[28:29]
	v_mov_b64_e32 v[14:15], v[30:31]
	v_mov_b64_e32 v[16:17], v[32:33]
	v_readlane_b32 s65, v254, 3
	v_readlane_b32 s66, v254, 4
	v_readlane_b32 s67, v254, 5
	v_readlane_b32 s72, v254, 10
	v_readlane_b32 s73, v254, 11
	v_readlane_b32 s74, v254, 12
	v_readlane_b32 s75, v254, 13
	v_readlane_b32 s76, v254, 14
	v_readlane_b32 s77, v254, 15
	v_readlane_b32 s78, v254, 16
	v_readlane_b32 s79, v254, 17
	global_load_dwordx4 v[216:219], v248, s[98:99] nt
	s_add_u32 s98, s98, 0x10000
	s_addc_u32 s99, s99, 0
	global_load_dwordx4 v[220:223], v248, s[100:101] nt
	s_add_u32 s100, s100, 0x10000
	s_addc_u32 s101, s101, 0
	global_load_dwordx4 v[224:227], v248, s[98:99] nt
	s_add_u32 s98, s98, 0x10000
	s_addc_u32 s99, s99, 0
	global_load_dwordx4 v[228:231], v248, s[100:101] nt
	s_add_u32 s100, s100, 0x10000
	s_addc_u32 s101, s101, 0
	global_load_dwordx4 v[232:235], v248, s[98:99] nt
	s_add_u32 s98, s98, 0x10000
	s_addc_u32 s99, s99, 0
	global_load_dwordx4 v[236:239], v248, s[100:101] nt
	s_add_u32 s100, s100, 0x10000
	s_addc_u32 s101, s101, 0
	global_load_dwordx4 v[240:243], v248, s[98:99] nt
	s_add_u32 s98, s98, 0x10000
	s_addc_u32 s99, s99, 0
	global_load_dwordx4 v[244:247], v248, s[100:101] nt
	s_add_u32 s100, s100, 0x10000
	s_addc_u32 s101, s101, 0
.LBB0_827:
	s_cmp_lg_u32 s16, 0x1000000
	s_cselect_b64 s[6:7], -1, 0
	s_cmp_eq_u32 s16, 0x1000000
	s_cselect_b64 s[18:19], -1, 0
	s_and_b64 vcc, exec, s[6:7]
	v_mov_b32_e32 v66, 0
	v_mov_b32_e32 v67, 0
	v_mov_b32_e32 v68, 0
	v_mov_b32_e32 v69, 0
	s_cbranch_vccnz .LBB0_829
	global_load_dwordx4 v[66:69], v[170:171], off

; #define LAS __attribute__((address_space(3)))
; DI unsigned cvtpk(float lo, float hi) { f32x2_t v = {lo, hi}; bf16x2_t b = __builtin_convertvector(v, bf16x2_t); return __builtin_bit_cast(unsigned, b); }
; #define DA_LOAD(st) do { const float* kb_ = Kc + (size_t)(st) * 131072; const float* vb_ = Vc + (size_t)(st) * 131072; \
;         _Pragma("unroll") for (int i = 0; i < 8; ++i) { kx[i] = __builtin_nontemporal_load((const v4f*)(kb_ + i * 16384 + voff)); vx[i] = __builtin_nontemporal_load((const v4f*)(vb_ + i * 16384 + voff)); } } while (0)
; DI void decode_unit(Ctx A_, LAS unsigned char* lds, int b, int h, float lam, int wave, int lane, int tid) {
;     ...
;         if (!last) {
; #pragma unroll
;             for (int i = 0; i < 8; ++i) {
;                 *(LAS v2u*)(kw + (i >> 1) * KR + (i & 1) * 256) = (v2u){fa::cvtpk(kx[i].x, kx[i].y), fa::cvtpk(kx[i].z, kx[i].w)};
;                 *(LAS v2u*)(vw + (i >> 1) * VR + (i & 1) * 1024) = (v2u){fa::cvtpk(vx[i].x, vx[i].y), fa::cvtpk(vx[i].z, vx[i].w)}; }
;             if (st + 1 < PAST / 128) DA_LOAD(st + 1);
.LBB0_835:
	s_andn2_b64 vcc, exec, s[20:21]
	s_cbranch_vccnz .LBB0_838
	s_cmp_eq_u32 s62, 30
	s_cbranch_scc1 .Ldr_t30
	s_cmp_eq_u32 s62, 31
	s_cbranch_scc1 .Ldr_t31
	s_mul_i32 s20, s62, 0xaaab
	s_lshr_b32 s20, s20, 17
	s_mul_i32 s20, s20, 3
	s_sub_i32 s20, s62, s20
	s_cmp_eq_u32 s20, 1
	s_cbranch_scc1 .Ldr_p1
	s_cmp_eq_u32 s20, 2
	s_cbranch_scc1 .Ldr_p2
.Ldr_p0:
	s_waitcnt vmcnt(23)
	v_cvt_pk_bf16_f32 v66, v82, v83
	v_cvt_pk_bf16_f32 v67, v84, v85
	ds_write_b64 v185, v[66:67]
	global_load_dwordx4 v[82:85], v248, s[98:99] nt
	s_add_u32 s98, s98, 0x10000
	s_addc_u32 s99, s99, 0
	s_waitcnt vmcnt(23)
	v_cvt_pk_bf16_f32 v66, v86, v87
	v_cvt_pk_bf16_f32 v67, v88, v89
	ds_write_b64 v186, v[66:67] offset:34816
	global_load_dwordx4 v[86:89], v248, s[100:101] nt
	s_add_u32 s100, s100, 0x10000
	s_addc_u32 s101, s101, 0
	s_waitcnt vmcnt(23)
	v_cvt_pk_bf16_f32 v66, v90, v91
	v_cvt_pk_bf16_f32 v67, v92, v93
	ds_write_b64 v185, v[66:67] offset:256
	global_load_dwordx4 v[90:93], v248, s[98:99] nt
	s_add_u32 s98, s98, 0x10000
	s_addc_u32 s99, s99, 0
	s_waitcnt vmcnt(23)
	v_cvt_pk_bf16_f32 v66, v94, v95
	v_cvt_pk_bf16_f32 v67, v96, v97
	ds_write_b64 v186, v[66:67] offset:35840
	global_load_dwordx4 v[94:97], v248, s[100:101] nt
	s_add_u32 s100, s100, 0x10000
	s_addc_u32 s101, s101, 0
	s_waitcnt vmcnt(23)
	v_cvt_pk_bf16_f32 v66, v98, v99
	v_cvt_pk_bf16_f32 v67, v100, v101
	ds_write_b64 v185, v[66:67] offset:8448
	global_load_dwordx4 v[98:101], v248, s[98:99] nt
	s_add_u32 s98, s98, 0x10000
	s_addc_u32 s99, s99, 0
	s_waitcnt vmcnt(23)
	v_cvt_pk_bf16_f32 v66, v102, v103
	v_cvt_pk_bf16_f32 v67, v104, v105
	ds_write_b64 v186, v[66:67] offset:43136
	global_load_dwordx4 v[102:105], v248, s[100:101] nt
	s_add_u32 s100, s100, 0x10000
	s_addc_u32 s101, s101, 0
	s_waitcnt vmcnt(23)
	v_cvt_pk_bf16_f32 v66, v106, v107
	v_cvt_pk_bf16_f32 v67, v108, v109
	ds_write_b64 v185, v[66:67] offset:8704
	global_load_dwordx4 v[106:109], v248, s[98:99] nt
	s_add_u32 s98, s98, 0x10000
	s_addc_u32 s99, s99, 0
	s_waitcnt vmcnt(23)
	v_cvt_pk_bf16_f32 v66, v110, v111
	v_cvt_pk_bf16_f32 v67, v112, v113
	ds_write_b64 v186, v[66:67] offset:44160
	global_load_dwordx4 v[110:113], v248, s[100:101] nt
	s_add_u32 s100, s100, 0x10000
	s_addc_u32 s101, s101, 0
	s_waitcnt vmcnt(23)
	v_cvt_pk_bf16_f32 v66, v114, v115
	v_cvt_pk_bf16_f32 v67, v116, v117
	ds_write_b64 v185, v[66:67] offset:16896
	global_load_dwordx4 v[114:117], v248, s[98:99] nt
	s_add_u32 s98, s98, 0x10000
	s_addc_u32 s99, s99, 0
	s_waitcnt vmcnt(23)
	v_cvt_pk_bf16_f32 v66, v118, v119
	v_cvt_pk_bf16_f32 v67, v120, v121
	ds_write_b64 v186, v[66:67] offset:51456
	global_load_dwordx4 v[118:121], v248, s[100:101] nt
	s_add_u32 s100, s100, 0x10000
	s_addc_u32 s101, s101, 0
	s_waitcnt vmcnt(23)
	v_cvt_pk_bf16_f32 v66, v130, v131
	v_cvt_pk_bf16_f32 v67, v132, v133
	ds_write_b64 v185, v[66:67] offset:17152
	global_load_dwordx4 v[130:133], v248, s[98:99] nt
	s_add_u32 s98, s98, 0x10000
	s_addc_u32 s99, s99, 0
	s_waitcnt vmcnt(23)
	v_cvt_pk_bf16_f32 v66, v138, v139
	v_cvt_pk_bf16_f32 v67, v140, v141
	ds_write_b64 v186, v[66:67] offset:52480
	global_load_dwordx4 v[138:141], v248, s[100:101] nt
	s_add_u32 s100, s100, 0x10000
	s_addc_u32 s101, s101, 0
	s_waitcnt vmcnt(23)
	v_cvt_pk_bf16_f32 v66, v146, v147
	v_cvt_pk_bf16_f32 v67, v148, v149
	ds_write_b64 v185, v[66:67] offset:25344
	global_load_dwordx4 v[146:149], v248, s[98:99] nt
	s_add_u32 s98, s98, 0x10000
	s_addc_u32 s99, s99, 0
	s_waitcnt vmcnt(23)
	v_cvt_pk_bf16_f32 v66, v150, v151
	v_cvt_pk_bf16_f32 v67, v152, v153
	ds_write_b64 v186, v[66:67] offset:59776
	global_load_dwordx4 v[150:153], v248, s[100:101] nt
	s_add_u32 s100, s100, 0x10000
	s_addc_u32 s101, s101, 0
	s_waitcnt vmcnt(23)
	v_cvt_pk_bf16_f32 v66, v154, v155
	v_cvt_pk_bf16_f32 v67, v156, v157
	ds_write_b64 v185, v[66:67] offset:25600
	global_load_dwordx4 v[154:157], v248, s[98:99] nt
	s_add_u32 s98, s98, 0x10000
	s_addc_u32 s99, s99, 0
	s_waitcnt vmcnt(23)
	v_cvt_pk_bf16_f32 v66, v158, v159
	v_cvt_pk_bf16_f32 v67, v160, v161
	ds_write_b64 v186, v[66:67] offset:60800
	global_load_dwordx4 v[158:161], v248, s[100:101] nt
	s_add_u32 s100, s100, 0x10000
	s_addc_u32 s101, s101, 0
	s_branch .LBB0_838
.Ldr_p1:
	s_waitcnt vmcnt(23)
	v_cvt_pk_bf16_f32 v66, v216, v217
	v_cvt_pk_bf16_f32 v67, v218, v219
	ds_write_b64 v185, v[66:67]
	global_load_dwordx4 v[216:219], v248, s[98:99] nt
	s_add_u32 s98, s98, 0x10000
	s_addc_u32 s99, s99, 0
	s_waitcnt vmcnt(23)
	v_cvt_pk_bf16_f32 v66, v220, v221
	v_cvt_pk_bf16_f32 v67, v222, v223
	ds_write_b64 v186, v[66:67] offset:34816
	global_load_dwordx4 v[220:223], v248, s[100:101] nt
	s_add_u32 s100, s100, 0x10000
	s_addc_u32 s101, s101, 0
	s_waitcnt vmcnt(23)
	v_cvt_pk_bf16_f32 v66, v224, v225
	v_cvt_pk_bf16_f32 v67, v226, v227
	ds_write_b64 v185, v[66:67] offset:256
	global_load_dwordx4 v[224:227], v248, s[98:99] nt
	s_add_u32 s98, s98, 0x10000
	s_addc_u32 s99, s99, 0
	s_waitcnt vmcnt(23)
	v_cvt_pk_bf16_f32 v66, v228, v229
	v_cvt_pk_bf16_f32 v67, v230, v231
	ds_write_b64 v186, v[66:67] offset:35840
	global_load_dwordx4 v[228:231], v248, s[100:101] nt
	s_add_u32 s100, s100, 0x10000
	s_addc_u32 s101, s101, 0
	s_waitcnt vmcnt(23)
	v_cvt_pk_bf16_f32 v66, v232, v233
	v_cvt_pk_bf16_f32 v67, v234, v235
	ds_write_b64 v185, v[66:67] offset:8448
	global_load_dwordx4 v[232:235], v248, s[98:99] nt
	s_add_u32 s98, s98, 0x10000
	s_addc_u32 s99, s99, 0
	s_waitcnt vmcnt(23)
	v_cvt_pk_bf16_f32 v66, v236, v237
	v_cvt_pk_bf16_f32 v67, v238, v239
	ds_write_b64 v186, v[66:67] offset:43136
	global_load_dwordx4 v[236:239], v248, s[100:101] nt
	s_add_u32 s100, s100, 0x10000
	s_addc_u32 s101, s101, 0
	s_waitcnt vmcnt(23)
; #define LAS __attribute__((address_space(3)))
; DI unsigned cvtpk(float lo, float hi) { f32x2_t v = {lo, hi}; bf16x2_t b = __builtin_convertvector(v, bf16x2_t); return __builtin_bit_cast(unsigned, b); }
; #define DA_LOAD(st) do { const float* kb_ = Kc + (size_t)(st) * 131072; const float* vb_ = Vc + (size_t)(st) * 131072; \
;         _Pragma("unroll") for (int i = 0; i < 8; ++i) { kx[i] = __builtin_nontemporal_load((const v4f*)(kb_ + i * 16384 + voff)); vx[i] = __builtin_nontemporal_load((const v4f*)(vb_ + i * 16384 + voff)); } } while (0)
; DI void decode_unit(Ctx A_, LAS unsigned char* lds, int b, int h, float lam, int wave, int lane, int tid) {
;     ...
;         if (!last) {
; #pragma unroll
;             for (int i = 0; i < 8; ++i) {
;                 *(LAS v2u*)(kw + (i >> 1) * KR + (i & 1) * 256) = (v2u){fa::cvtpk(kx[i].x, kx[i].y), fa::cvtpk(kx[i].z, kx[i].w)};
;                 *(LAS v2u*)(vw + (i >> 1) * VR + (i & 1) * 1024) = (v2u){fa::cvtpk(vx[i].x, vx[i].y), fa::cvtpk(vx[i].z, vx[i].w)}; }
;             if (st + 1 < PAST / 128) DA_LOAD(st + 1);
	v_cvt_pk_bf16_f32 v66, v240, v241
	v_cvt_pk_bf16_f32 v67, v242, v243
	ds_write_b64 v185, v[66:67] offset:8704
	global_load_dwordx4 v[240:243], v248, s[98:99] nt
	s_add_u32 s98, s98, 0x10000
	s_addc_u32 s99, s99, 0
	s_waitcnt vmcnt(23)
	v_cvt_pk_bf16_f32 v66, v244, v245
	v_cvt_pk_bf16_f32 v67, v246, v247
	ds_write_b64 v186, v[66:67] offset:44160
	global_load_dwordx4 v[244:247], v248, s[100:101] nt
	s_add_u32 s100, s100, 0x10000
	s_addc_u32 s101, s101, 0
	s_waitcnt vmcnt(23)
	v_cvt_pk_bf16_f32 v66, v82, v83
	v_cvt_pk_bf16_f32 v67, v84, v85
	ds_write_b64 v185, v[66:67] offset:16896
	global_load_dwordx4 v[82:85], v248, s[98:99] nt
	s_add_u32 s98, s98, 0x10000
	s_addc_u32 s99, s99, 0
	s_waitcnt vmcnt(23)
	v_cvt_pk_bf16_f32 v66, v86, v87
	v_cvt_pk_bf16_f32 v67, v88, v89
	ds_write_b64 v186, v[66:67] offset:51456
	global_load_dwordx4 v[86:89], v248, s[100:101] nt
	s_add_u32 s100, s100, 0x10000
	s_addc_u32 s101, s101, 0
	s_waitcnt vmcnt(23)
	v_cvt_pk_bf16_f32 v66, v90, v91
	v_cvt_pk_bf16_f32 v67, v92, v93
	ds_write_b64 v185, v[66:67] offset:17152
	global_load_dwordx4 v[90:93], v248, s[98:99] nt
	s_add_u32 s98, s98, 0x10000
	s_addc_u32 s99, s99, 0
	s_waitcnt vmcnt(23)
	v_cvt_pk_bf16_f32 v66, v94, v95
	v_cvt_pk_bf16_f32 v67, v96, v97
	ds_write_b64 v186, v[66:67] offset:52480
	global_load_dwordx4 v[94:97], v248, s[100:101] nt
	s_add_u32 s100, s100, 0x10000
	s_addc_u32 s101, s101, 0
	s_waitcnt vmcnt(23)
	v_cvt_pk_bf16_f32 v66, v98, v99
	v_cvt_pk_bf16_f32 v67, v100, v101
	ds_write_b64 v185, v[66:67] offset:25344
	global_load_dwordx4 v[98:101], v248, s[98:99] nt
	s_add_u32 s98, s98, 0x10000
	s_addc_u32 s99, s99, 0
	s_waitcnt vmcnt(23)
	v_cvt_pk_bf16_f32 v66, v102, v103
	v_cvt_pk_bf16_f32 v67, v104, v105
	ds_write_b64 v186, v[66:67] offset:59776
	global_load_dwordx4 v[102:105], v248, s[100:101] nt
	s_add_u32 s100, s100, 0x10000
	s_addc_u32 s101, s101, 0
	s_waitcnt vmcnt(23)
	v_cvt_pk_bf16_f32 v66, v106, v107
	v_cvt_pk_bf16_f32 v67, v108, v109
	ds_write_b64 v185, v[66:67] offset:25600
	global_load_dwordx4 v[106:109], v248, s[98:99] nt
	s_add_u32 s98, s98, 0x10000
	s_addc_u32 s99, s99, 0
	s_waitcnt vmcnt(23)
	v_cvt_pk_bf16_f32 v66, v110, v111
	v_cvt_pk_bf16_f32 v67, v112, v113
	ds_write_b64 v186, v[66:67] offset:60800
	global_load_dwordx4 v[110:113], v248, s[100:101] nt
	s_add_u32 s100, s100, 0x10000
	s_addc_u32 s101, s101, 0
	s_branch .LBB0_838
.Ldr_p2:
	s_waitcnt vmcnt(23)
	v_cvt_pk_bf16_f32 v66, v114, v115
	v_cvt_pk_bf16_f32 v67, v116, v117
	ds_write_b64 v185, v[66:67]
	global_load_dwordx4 v[114:117], v248, s[98:99] nt
	s_add_u32 s98, s98, 0x10000
	s_addc_u32 s99, s99, 0
	s_waitcnt vmcnt(23)
	v_cvt_pk_bf16_f32 v66, v118, v119
	v_cvt_pk_bf16_f32 v67, v120, v121
	ds_write_b64 v186, v[66:67] offset:34816
	global_load_dwordx4 v[118:121], v248, s[100:101] nt
	s_add_u32 s100, s100, 0x10000
	s_addc_u32 s101, s101, 0
	s_waitcnt vmcnt(23)
	v_cvt_pk_bf16_f32 v66, v130, v131
	v_cvt_pk_bf16_f32 v67, v132, v133
	ds_write_b64 v185, v[66:67] offset:256
	global_load_dwordx4 v[130:133], v248, s[98:99] nt
	s_add_u32 s98, s98, 0x10000
	s_addc_u32 s99, s99, 0
	s_waitcnt vmcnt(23)
	v_cvt_pk_bf16_f32 v66, v138, v139
	v_cvt_pk_bf16_f32 v67, v140, v141
	ds_write_b64 v186, v[66:67] offset:35840
	global_load_dwordx4 v[138:141], v248, s[100:101] nt
	s_add_u32 s100, s100, 0x10000
	s_addc_u32 s101, s101, 0
	s_waitcnt vmcnt(23)
	v_cvt_pk_bf16_f32 v66, v146, v147
	v_cvt_pk_bf16_f32 v67, v148, v149
	ds_write_b64 v185, v[66:67] offset:8448
	global_load_dwordx4 v[146:149], v248, s[98:99] nt
	s_add_u32 s98, s98, 0x10000
	s_addc_u32 s99, s99, 0
	s_waitcnt vmcnt(23)
	v_cvt_pk_bf16_f32 v66, v150, v151
	v_cvt_pk_bf16_f32 v67, v152, v153
	ds_write_b64 v186, v[66:67] offset:43136
	global_load_dwordx4 v[150:153], v248, s[100:101] nt
	s_add_u32 s100, s100, 0x10000
	s_addc_u32 s101, s101, 0
	s_waitcnt vmcnt(23)
	v_cvt_pk_bf16_f32 v66, v154, v155
	v_cvt_pk_bf16_f32 v67, v156, v157
	ds_write_b64 v185, v[66:67] offset:8704
	global_load_dwordx4 v[154:157], v248, s[98:99] nt
	s_add_u32 s98, s98, 0x10000
	s_addc_u32 s99, s99, 0
	s_waitcnt vmcnt(23)
	v_cvt_pk_bf16_f32 v66, v158, v159
	v_cvt_pk_bf16_f32 v67, v160, v161
	ds_write_b64 v186, v[66:67] offset:44160
	global_load_dwordx4 v[158:161], v248, s[100:101] nt
	s_add_u32 s100, s100, 0x10000
	s_addc_u32 s101, s101, 0
	s_waitcnt vmcnt(23)
	v_cvt_pk_bf16_f32 v66, v216, v217
	v_cvt_pk_bf16_f32 v67, v218, v219
	ds_write_b64 v185, v[66:67] offset:16896
	global_load_dwordx4 v[216:219], v248, s[98:99] nt
	s_add_u32 s98, s98, 0x10000
	s_addc_u32 s99, s99, 0
	s_waitcnt vmcnt(23)
	v_cvt_pk_bf16_f32 v66, v220, v221
	v_cvt_pk_bf16_f32 v67, v222, v223
	ds_write_b64 v186, v[66:67] offset:51456
	global_load_dwordx4 v[220:223], v248, s[100:101] nt
	s_add_u32 s100, s100, 0x10000
	s_addc_u32 s101, s101, 0
	s_waitcnt vmcnt(23)
	v_cvt_pk_bf16_f32 v66, v224, v225
	v_cvt_pk_bf16_f32 v67, v226, v227
	ds_write_b64 v185, v[66:67] offset:17152
	global_load_dwordx4 v[224:227], v248, s[98:99] nt
	s_add_u32 s98, s98, 0x10000
	s_addc_u32 s99, s99, 0
	s_waitcnt vmcnt(23)
	v_cvt_pk_bf16_f32 v66, v228, v229
	v_cvt_pk_bf16_f32 v67, v230, v231
	ds_write_b64 v186, v[66:67] offset:52480
	global_load_dwordx4 v[228:231], v248, s[100:101] nt
	s_add_u32 s100, s100, 0x10000
	s_addc_u32 s101, s101, 0
	s_waitcnt vmcnt(23)
	v_cvt_pk_bf16_f32 v66, v232, v233
	v_cvt_pk_bf16_f32 v67, v234, v235
	ds_write_b64 v185, v[66:67] offset:25344
	global_load_dwordx4 v[232:235], v248, s[98:99] nt
	s_add_u32 s98, s98, 0x10000
	s_addc_u32 s99, s99, 0
	s_waitcnt vmcnt(23)
	v_cvt_pk_bf16_f32 v66, v236, v237
	v_cvt_pk_bf16_f32 v67, v238, v239
	ds_write_b64 v186, v[66:67] offset:59776
	global_load_dwordx4 v[236:239], v248, s[100:101] nt
	s_add_u32 s100, s100, 0x10000
	s_addc_u32 s101, s101, 0
	s_waitcnt vmcnt(23)
	v_cvt_pk_bf16_f32 v66, v240, v241
	v_cvt_pk_bf16_f32 v67, v242, v243
	ds_write_b64 v185, v[66:67] offset:25600
	global_load_dwordx4 v[240:243], v248, s[98:99] nt
	s_add_u32 s98, s98, 0x10000
	s_addc_u32 s99, s99, 0
	s_waitcnt vmcnt(23)
	v_cvt_pk_bf16_f32 v66, v244, v245
	v_cvt_pk_bf16_f32 v67, v246, v247
	ds_write_b64 v186, v[66:67] offset:60800
	global_load_dwordx4 v[244:247], v248, s[100:101] nt
	s_add_u32 s100, s100, 0x10000
	s_addc_u32 s101, s101, 0
	s_branch .LBB0_838
; #define LAS __attribute__((address_space(3)))
; DI unsigned cvtpk(float lo, float hi) { f32x2_t v = {lo, hi}; bf16x2_t b = __builtin_convertvector(v, bf16x2_t); return __builtin_bit_cast(unsigned, b); }
; #define DA_LOAD(st) do { const float* kb_ = Kc + (size_t)(st) * 131072; const float* vb_ = Vc + (size_t)(st) * 131072; \
;         _Pragma("unroll") for (int i = 0; i < 8; ++i) { kx[i] = __builtin_nontemporal_load((const v4f*)(kb_ + i * 16384 + voff)); vx[i] = __builtin_nontemporal_load((const v4f*)(vb_ + i * 16384 + voff)); } } while (0)
; DI void decode_unit(Ctx A_, LAS unsigned char* lds, int b, int h, float lam, int wave, int lane, int tid) {
;     ...
;         if (!last) {
; #pragma unroll
;             for (int i = 0; i < 8; ++i) {
;                 *(LAS v2u*)(kw + (i >> 1) * KR + (i & 1) * 256) = (v2u){fa::cvtpk(kx[i].x, kx[i].y), fa::cvtpk(kx[i].z, kx[i].w)};
;                 *(LAS v2u*)(vw + (i >> 1) * VR + (i & 1) * 1024) = (v2u){fa::cvtpk(vx[i].x, vx[i].y), fa::cvtpk(vx[i].z, vx[i].w)}; }
;             if (st + 1 < PAST / 128) DA_LOAD(st + 1);
.Ldr_t30:
	s_waitcnt vmcnt(0)
	v_cvt_pk_bf16_f32 v66, v82, v83
	v_cvt_pk_bf16_f32 v67, v84, v85
	ds_write_b64 v185, v[66:67]
	global_load_dwordx4 v[82:85], v248, s[98:99] nt
	s_add_u32 s98, s98, 0x10000
	s_addc_u32 s99, s99, 0
	v_cvt_pk_bf16_f32 v66, v86, v87
	v_cvt_pk_bf16_f32 v67, v88, v89
	ds_write_b64 v186, v[66:67] offset:34816
	global_load_dwordx4 v[86:89], v248, s[100:101] nt
	s_add_u32 s100, s100, 0x10000
	s_addc_u32 s101, s101, 0
	v_cvt_pk_bf16_f32 v66, v90, v91
	v_cvt_pk_bf16_f32 v67, v92, v93
	ds_write_b64 v185, v[66:67] offset:256
	global_load_dwordx4 v[90:93], v248, s[98:99] nt
	s_add_u32 s98, s98, 0x10000
	s_addc_u32 s99, s99, 0
	v_cvt_pk_bf16_f32 v66, v94, v95
	v_cvt_pk_bf16_f32 v67, v96, v97
	ds_write_b64 v186, v[66:67] offset:35840
	global_load_dwordx4 v[94:97], v248, s[100:101] nt
	s_add_u32 s100, s100, 0x10000
	s_addc_u32 s101, s101, 0
	v_cvt_pk_bf16_f32 v66, v98, v99
	v_cvt_pk_bf16_f32 v67, v100, v101
	ds_write_b64 v185, v[66:67] offset:8448
	global_load_dwordx4 v[98:101], v248, s[98:99] nt
	s_add_u32 s98, s98, 0x10000
	s_addc_u32 s99, s99, 0
	v_cvt_pk_bf16_f32 v66, v102, v103
	v_cvt_pk_bf16_f32 v67, v104, v105
	ds_write_b64 v186, v[66:67] offset:43136
	global_load_dwordx4 v[102:105], v248, s[100:101] nt
	s_add_u32 s100, s100, 0x10000
	s_addc_u32 s101, s101, 0
	v_cvt_pk_bf16_f32 v66, v106, v107
	v_cvt_pk_bf16_f32 v67, v108, v109
	ds_write_b64 v185, v[66:67] offset:8704
	global_load_dwordx4 v[106:109], v248, s[98:99] nt
	s_add_u32 s98, s98, 0x10000
	s_addc_u32 s99, s99, 0
	v_cvt_pk_bf16_f32 v66, v110, v111
	v_cvt_pk_bf16_f32 v67, v112, v113
	ds_write_b64 v186, v[66:67] offset:44160
	global_load_dwordx4 v[110:113], v248, s[100:101] nt
	s_add_u32 s100, s100, 0x10000
	s_addc_u32 s101, s101, 0
	v_cvt_pk_bf16_f32 v66, v114, v115
	v_cvt_pk_bf16_f32 v67, v116, v117
	ds_write_b64 v185, v[66:67] offset:16896
	v_cvt_pk_bf16_f32 v66, v118, v119
	v_cvt_pk_bf16_f32 v67, v120, v121
	ds_write_b64 v186, v[66:67] offset:51456
	v_cvt_pk_bf16_f32 v66, v130, v131
	v_cvt_pk_bf16_f32 v67, v132, v133
	ds_write_b64 v185, v[66:67] offset:17152
	v_cvt_pk_bf16_f32 v66, v138, v139
	v_cvt_pk_bf16_f32 v67, v140, v141
	ds_write_b64 v186, v[66:67] offset:52480
	v_cvt_pk_bf16_f32 v66, v146, v147
	v_cvt_pk_bf16_f32 v67, v148, v149
	ds_write_b64 v185, v[66:67] offset:25344
	v_cvt_pk_bf16_f32 v66, v150, v151
	v_cvt_pk_bf16_f32 v67, v152, v153
	ds_write_b64 v186, v[66:67] offset:59776
	v_cvt_pk_bf16_f32 v66, v154, v155
	v_cvt_pk_bf16_f32 v67, v156, v157
	ds_write_b64 v185, v[66:67] offset:25600
	v_cvt_pk_bf16_f32 v66, v158, v159
	v_cvt_pk_bf16_f32 v67, v160, v161
	ds_write_b64 v186, v[66:67] offset:60800
	s_branch .LBB0_838
.Ldr_t31:
	s_waitcnt vmcnt(0)
	v_cvt_pk_bf16_f32 v66, v216, v217
	v_cvt_pk_bf16_f32 v67, v218, v219
	ds_write_b64 v185, v[66:67]
	v_cvt_pk_bf16_f32 v66, v220, v221
	v_cvt_pk_bf16_f32 v67, v222, v223
	ds_write_b64 v186, v[66:67] offset:34816
	v_cvt_pk_bf16_f32 v66, v224, v225
	v_cvt_pk_bf16_f32 v67, v226, v227
	ds_write_b64 v185, v[66:67] offset:256
	v_cvt_pk_bf16_f32 v66, v228, v229
	v_cvt_pk_bf16_f32 v67, v230, v231
	ds_write_b64 v186, v[66:67] offset:35840
	v_cvt_pk_bf16_f32 v66, v232, v233
	v_cvt_pk_bf16_f32 v67, v234, v235
	ds_write_b64 v185, v[66:67] offset:8448
	v_cvt_pk_bf16_f32 v66, v236, v237
	v_cvt_pk_bf16_f32 v67, v238, v239
	ds_write_b64 v186, v[66:67] offset:43136
	v_cvt_pk_bf16_f32 v66, v240, v241
	v_cvt_pk_bf16_f32 v67, v242, v243
	ds_write_b64 v185, v[66:67] offset:8704
	v_cvt_pk_bf16_f32 v66, v244, v245
	v_cvt_pk_bf16_f32 v67, v246, v247
	ds_write_b64 v186, v[66:67] offset:44160
	v_cvt_pk_bf16_f32 v66, v82, v83
	v_cvt_pk_bf16_f32 v67, v84, v85
	ds_write_b64 v185, v[66:67] offset:16896
	v_cvt_pk_bf16_f32 v66, v86, v87
	v_cvt_pk_bf16_f32 v67, v88, v89
	ds_write_b64 v186, v[66:67] offset:51456
	v_cvt_pk_bf16_f32 v66, v90, v91
	v_cvt_pk_bf16_f32 v67, v92, v93
	ds_write_b64 v185, v[66:67] offset:17152
	v_cvt_pk_bf16_f32 v66, v94, v95
	v_cvt_pk_bf16_f32 v67, v96, v97
	ds_write_b64 v186, v[66:67] offset:52480
	v_cvt_pk_bf16_f32 v66, v98, v99
	v_cvt_pk_bf16_f32 v67, v100, v101
	ds_write_b64 v185, v[66:67] offset:25344
	v_cvt_pk_bf16_f32 v66, v102, v103
	v_cvt_pk_bf16_f32 v67, v104, v105
	ds_write_b64 v186, v[66:67] offset:59776
	v_cvt_pk_bf16_f32 v66, v106, v107
	v_cvt_pk_bf16_f32 v67, v108, v109
	ds_write_b64 v185, v[66:67] offset:25600
	v_cvt_pk_bf16_f32 v66, v110, v111
	v_cvt_pk_bf16_f32 v67, v112, v113
	ds_write_b64 v186, v[66:67] offset:60800
	s_branch .LBB0_838

; DI float bf2f(unsigned short u) { return __uint_as_float((unsigned)u << 16); }
; DI unsigned f2bf(float f) { unsigned u = __float_as_uint(f); return (u + 0x7fffu + ((u >> 16) & 1u)) >> 16; }
; DI int crow(int i, int hh) { return (i & 3) + 8 * (i >> 2) + 4 * hh; }
; DI void decode_unit(Ctx A_, LAS unsigned char* lds, int b, int h, float lam, int wave, int lane, int tid) {
;     ...
;         for (int nb = 0; nb < 4; ++nb) { const float sn = SUB_NORM[nb * 32 + r_e];
; #pragma unroll
;             for (int i = 0; i < 8; ++i) { const size_t rw = rowq + crow(i, hh); Y_[rw * YLD + C_YA + h * 128 + nb * 32 + r_e] = (bf16)f2bf(acc[nb][i] * ssq[i] * sn * bf2f(P[rw * PLD + C_ZA + h * 128 + nb * 32 + r_e])); } }
.LBB0_848:
	v_readfirstlane_b32 s101, v208
	v_readfirstlane_b32 s98, v0
	s_cmpk_gt_u32 s98, 63
	s_cbranch_scc1 .Ldec_touch_skip
	s_lshr_b32 s98, s101, 3
	s_lshl_b32 s98, s98, 4
	s_add_u32 s98, s98, 0x8000
	s_mul_hi_u32 s99, s98, 0x5800
	s_mul_i32 s98, s98, 0x5800
	v_readlane_b32 s100, v255, 9
	v_and_b32_e32 v206, 63, v0
	s_add_u32 s98, s98, s100
	v_readlane_b32 s100, v255, 10
	v_lshrrev_b32_e32 v207, 1, v206
	s_addc_u32 s99, s99, s100
	s_and_b32 s100, s101, 7
	s_lshl_b32 s100, s100, 8
	s_addk_i32 s100, 0x1800
	s_add_u32 s98, s98, s100
	s_addc_u32 s99, s99, 0
	v_mul_u32_u24_e32 v207, 0x5800, v207
	v_and_b32_e32 v206, 1, v206
	v_lshl_or_b32 v206, v206, 7, v207
	s_nop 0
	global_load_dword v207, v206, s[98:99]
